# rg output tile final stage: 4 channels per lane, DPP row reduction for the RMS norm, dwordx2 gate loads and stores
# speedup vs baseline: 1.0655x; 1.0017x over previous
; __device__ void rg_tile(unsigned char* lds, const Params& p, int l, int b, int ck, int hh, bool outmode) {
;     ...
;   const int tid = opaque_tid(), lane = tid & 63, w = tid >> 6, lr = lane & 15, lg = lane >> 4;
;   const bf16_t* z = (const bf16_t*)(p.ws + OFF_A);
;   bf16_t* y = (bf16_t*)(p.ws + OFF_ACT);
;   float* agg = (float*)(p.ws + OFF_RGAGG);
;   const float* car = (const float*)(p.ws + OFF_RGCAR);
;   const bool isctx = ck < 4;
;   const int L = isctx ? 256 : 2048;
;   const int t0 = isctx ? ck * 64 : (ck - 4) * 64;
;   const int rowbase = isctx ? (NLAT + b * 256) : (b * 2048);
;   float car_pre = 0.f, gp_pre[8];
;   {
;     const int d_ = (tid >> 6) & 1, j_ = tid & 63;
;     if (outmode) {
;       car_pre = car[((size_t)(b * 36 + ck) * 2 + d_) * 256 + hh * 64 + j_];
; #pragma unroll
;       for (int q = 0; q < 8; ++q) gp_pre[q] = bf2f(z[(size_t)(rowbase + t0 + w * 8 + q) * ZS + 2816 + 256 + hh * 64 + lane]);
;     } else {
; #pragma unroll
;       for (int q = 0; q < 8; ++q) gp_pre[q] = 0.f;
;     }
;   }
;   const int chm_ = hh * 64 + (w & 3) * 16 + lr, dm_ = w >> 2;
;   const float br = p.in[22][(size_t)l * 1024 + (dm_ * 2 + 0) * 256 + chm_];
;   const float bi = p.in[22][(size_t)l * 1024 + (dm_ * 2 + 1) * 256 + chm_];
;   const float lam_ = p.in[23][(size_t)l * 512 + dm_ * 256 + chm_];
;   {
;     const int i = tid & 63, tq = tid >> 6;
;     const int ch = hh * 64 + i;
;     const float* wc = p.in[20] + (size_t)l * 4 * 256 + ch;
;     const float w0 = wc[0], w1 = wc[256], w2 = wc[512], w3 = wc[768];
; #pragma unroll
;     for (int ii = 0; ii < 8; ++ii) {
;       const int tt = tq * 8 + ii;
;       const int tp = t0 + tt;
;       const int tm1 = tp - 1 >= 0 ? tp - 1 : 0, tp1 = tp + 1 < L ? tp + 1 : L - 1, tp2 = tp + 2 < L ? tp + 2 : L - 1;
;       const float z0 = bf2f(z[(size_t)(rowbase + tm1) * ZS + 2816 + ch]);
;       const float z1 = bf2f(z[(size_t)(rowbase + tp) * ZS + 2816 + ch]);
;       const float z2 = bf2f(z[(size_t)(rowbase + tp1) * ZS + 2816 + ch]);
;       const float z3 = bf2f(z[(size_t)(rowbase + tp2) * ZS + 2816 + ch]);
;       float xr = w1 * z1;
;       xr += (tp - 1 >= 0 ? w0 : 0.f) * z0;
;       xr += (tp + 1 < L ? w2 : 0.f) * z2;
;       xr += (tp + 2 < L ? w3 : 0.f) * z3;
;       XR[tt * 65 + i] = xr;
;       XB[tt * 72 + i] = f2bf(xr);
;     }
.LBB0_708:
	s_and_b64 vcc, exec, s[0:1]
	s_cbranch_vccz .LBB0_812
	s_sub_i32 s0, s13, s30
	s_ashr_i32 s2, s0, 2
	s_abs_i32 s2, s2
	v_readlane_b32 s3, v254, 14
	s_mul_hi_u32 s3, s2, s3
	v_readlane_b32 s4, v254, 11
	s_mul_i32 s3, s3, s4
	s_sub_i32 s2, s2, s3
	s_and_b32 s1, s13, 3
	s_sub_i32 s3, s2, s4
	s_cmp_ge_u32 s2, s4
	s_cselect_b32 s2, s3, s2
	s_sub_i32 s3, s2, s4
	s_cmp_ge_u32 s2, s4
	s_cselect_b32 s2, s3, s2
	s_ashr_i32 s3, s0, 31
	s_xor_b32 s2, s2, s3
	s_sub_i32 s2, s2, s3
	v_readlane_b32 s4, v254, 22
	s_add_i32 s4, s2, s4
	s_abs_i32 s0, s0
	v_readlane_b32 s2, v254, 16
	s_mul_hi_u32 s2, s0, s2
	v_readlane_b32 s7, v254, 15
	s_mul_i32 s5, s2, s7
	s_sub_i32 s0, s0, s5
	s_add_i32 s5, s2, 1
	s_sub_i32 s6, s0, s7
	s_cmp_ge_u32 s0, s7
	s_cselect_b32 s2, s5, s2
	s_cselect_b32 s0, s6, s0
	s_add_i32 s5, s2, 1
	s_cmp_ge_u32 s0, s7
	s_cselect_b32 s0, s5, s2
	s_xor_b32 s0, s0, s3
	s_sub_i32 s5, s0, s3
	s_lshl_b32 s2, s4, 6
	s_lshl_b32 s0, s5, 8
	s_add_i32 s3, s2, 0xffffff00
	s_add_i32 s6, s0, 0x4000
	s_lshl_b32 s7, s5, 11
	s_cmp_lt_i32 s4, 4
	s_movk_i32 s0, 0x800
	s_mul_i32 s5, s5, 36
	s_cselect_b32 s0, 0x100, s0
	s_cselect_b32 s3, s2, s3
	s_cselect_b32 s2, s6, s7
	s_add_i32 s4, s5, s4
	v_mov_b32_e32 v52, v195
	v_readfirstlane_b32 s44, v195
	s_mov_b32 s47, s0
	s_mov_b32 s48, s2
	s_mov_b32 s49, s3
	s_lshl_b32 s50, s1, 7
	s_lshr_b32 s44, s44, 6
	s_lshl_b32 s45, s44, 3
	s_add_i32 s45, s45, s49
	s_add_i32 s46, s47, -1
	s_addk_i32 s50, 0x1600
	v_and_b32_e32 v185, 63, v195
	v_lshl_add_u32 v180, v185, 1, s50
	v_readlane_b32 s52, v254, 3
	v_readlane_b32 s53, v254, 4
	s_lshl_b32 s51, s1, 8
	v_lshl_add_u32 v181, v185, 2, s51
	s_nop 4
	global_load_dword v165, v181, s[52:53]
	global_load_dword v166, v181, s[52:53] offset:1024
	global_load_dword v167, v181, s[52:53] offset:2048
	global_load_dword v168, v181, s[52:53] offset:3072
	s_add_i32 s54, s45, s48
	s_mul_i32 s54, s54, 0x1a00
	s_and_b32 s56, s13, 3
	v_bfe_u32 v208, v195, 4, 2
	v_and_b32_e32 v209, 15, v195
	v_mul_u32_u24_e32 v210, 0x1a00, v208
	v_lshl_add_u32 v210, v209, 3, v210
	s_add_i32 s57, s54, s50
	s_addk_i32 s57, 0x200
	v_add_u32_e32 v210, s57, v210
	v_readlane_b32 s58, v254, 9
	v_readlane_b32 s59, v254, 10
	global_load_dwordx2 v[204:205], v210, s[88:89]
	v_add_u32_e32 v210, 0x6800, v210
	global_load_dwordx2 v[206:207], v210, s[88:89]
	s_lshl_b32 s57, s56, 8
	s_addk_i32 s57, 0xc00
	v_lshl_add_u32 v211, v209, 4, s57
	s_nop 1
	global_load_dwordx4 v[200:203], v211, s[58:59]
	v_add_u32_e32 v181, s54, v180
	s_add_i32 s55, s45, -1
	s_max_i32 s55, s55, 0
	s_add_i32 s55, s55, s48
	s_mul_i32 s55, s55, 0x1a00
	v_add_u32_e32 v184, s55, v180
	global_load_ushort v154, v184, s[88:89]
	global_load_ushort v155, v181, s[88:89]
	v_add_u32_e32 v181, 0x1a00, v181
	global_load_ushort v156, v181, s[88:89]
	v_add_u32_e32 v181, 0x1a00, v181
	global_load_ushort v157, v181, s[88:89]
	v_add_u32_e32 v181, 0x1a00, v181
	global_load_ushort v158, v181, s[88:89]
	v_add_u32_e32 v181, 0x1a00, v181
	global_load_ushort v159, v181, s[88:89]
	v_add_u32_e32 v181, 0x1a00, v181
	global_load_ushort v160, v181, s[88:89]
	v_add_u32_e32 v181, 0x1a00, v181
	global_load_ushort v161, v181, s[88:89]
	v_add_u32_e32 v181, 0x1a00, v181
	global_load_ushort v162, v181, s[88:89]
	s_add_i32 s55, s45, 8
	s_min_i32 s55, s55, s46
	s_add_i32 s55, s55, s48
	s_mul_i32 s55, s55, 0x1a00
	v_add_u32_e32 v184, s55, v180
	global_load_ushort v163, v184, s[88:89]
	s_add_i32 s55, s45, 9
	s_min_i32 s55, s55, s46
	s_add_i32 s55, s55, s48
	s_mul_i32 s55, s55, 0x1a00
	v_add_u32_e32 v184, s55, v180
	global_load_ushort v164, v184, s[88:89]
	s_mul_i32 s55, s44, 0x820
	v_lshl_add_u32 v182, v185, 2, s55
	s_mul_i32 s55, s44, 0x480
	v_lshl_add_u32 v183, v185, 1, s55
	s_ashr_i32 s5, s4, 31
	s_lshl_b32 s7, s1, 6
	v_ashrrev_i32_e32 v47, 6, v52
	s_lshl_b64 s[4:5], s[4:5], 11
	v_readlane_b32 s8, v252, 11
	v_and_b32_e32 v48, 1, v47
	v_readlane_b32 s9, v252, 12
	s_add_u32 s4, s8, s4
	s_addc_u32 s5, s9, s5
	v_lshlrev_b32_e32 v192, 10, v48
	v_and_b32_e32 v29, 63, v52
	v_lshl_add_u64 v[0:1], s[4:5], 0, v[192:193]
	s_lshl_b32 s96, s1, 8
	v_lshl_add_u64 v[0:1], v[0:1], 0, s[96:97]
	v_lshlrev_b32_e32 v192, 2, v29
	s_add_i32 s4, s3, s2
	v_lshlrev_b32_e32 v12, 3, v47
	v_lshl_add_u64 v[2:3], v[0:1], 0, v[192:193]
	v_add_u32_e32 v28, s4, v12
	v_mov_b64_e32 v[0:1], s[88:89]
	s_lshl_b32 s96, s1, 7
	s_movk_i32 s10, 0x1000
	s_nop 0
	s_nop 0
	global_load_dword v51, v[2:3], off
	s_add_i32 s6, s2, -1
	v_or_b32_e32 v7, s7, v29
	v_lshlrev_b32_e32 v32, 1, v7
	v_mov_b32_e32 v33, v193
	v_lshlrev_b32_e32 v39, 2, v7
	s_add_i32 s5, s0, -1
	s_nop 0
	s_nop 0
	s_nop 0
	s_nop 0
	v_and_b32_e32 v6, 15, v52
	s_nop 0
	v_lshlrev_b32_e32 v2, 4, v47
	v_ashrrev_i32_e32 v56, 8, v52
	v_and_or_b32 v55, v2, 48, v6
	v_lshlrev_b32_e32 v2, 9, v56
	v_readlane_b32 s8, v254, 12
	v_lshl_or_b32 v7, v56, 1, 1
	v_or_b32_e32 v4, s7, v55
	v_ashrrev_i32_e32 v3, 31, v2
	v_readlane_b32 s9, v254, 13
	v_lshlrev_b32_e32 v16, 8, v7
	v_lshlrev_b32_e32 v4, 2, v4
	v_lshl_add_u64 v[2:3], v[2:3], 2, s[8:9]
	v_mov_b32_e32 v5, v193
	v_ashrrev_i32_e32 v17, 31, v16
	v_lshl_add_u64 v[2:3], v[2:3], 0, v[4:5]
	v_lshl_add_u64 v[16:17], v[16:17], 2, s[8:9]
	v_lshl_add_u64 v[16:17], v[16:17], 0, v[4:5]
	global_load_dword v54, v[2:3], off
	global_load_dword v53, v[16:17], off
	v_and_b32_e32 v2, 0xffffff00, v52
	v_readlane_b32 s8, v254, 1
	v_ashrrev_i32_e32 v3, 31, v2
	v_readlane_b32 s9, v254, 2
	v_or_b32_e32 v37, 1, v12
	v_add_u32_e32 v30, 0, v192
	v_lshl_add_u64 v[2:3], v[2:3], 2, s[8:9]
	v_lshl_add_u64 v[2:3], v[2:3], 0, v[4:5]
	global_load_dword v16, v[2:3], off
	s_nop 0
	s_nop 0
	v_or_b32_e32 v38, 2, v12
	s_nop 0
	v_or_b32_e32 v40, 3, v12
	s_nop 0
; __device__ __forceinline__ bf16_t f2bf(float f) { return (bf16_t)(pack2(f, 0.f) & 0xffffu); }
; __device__ __forceinline__ float bf2f(bf16_t h) { return __uint_as_float(((unsigned)h) << 16); }
; __device__ void rg_tile(unsigned char* lds, const Params& p, int l, int b, int ck, int hh, bool outmode) {
;     ...
;   {
;     const int i = tid & 63, tq = tid >> 6;
;     const int ch = hh * 64 + i;
;     const float* wc = p.in[20] + (size_t)l * 4 * 256 + ch;
;     const float w0 = wc[0], w1 = wc[256], w2 = wc[512], w3 = wc[768];
; #pragma unroll
;     for (int ii = 0; ii < 8; ++ii) {
;       const int tt = tq * 8 + ii;
;       const int tp = t0 + tt;
;       const int tm1 = tp - 1 >= 0 ? tp - 1 : 0, tp1 = tp + 1 < L ? tp + 1 : L - 1, tp2 = tp + 2 < L ? tp + 2 : L - 1;
;       const float z0 = bf2f(z[(size_t)(rowbase + tm1) * ZS + 2816 + ch]);
;       const float z1 = bf2f(z[(size_t)(rowbase + tp) * ZS + 2816 + ch]);
;       const float z2 = bf2f(z[(size_t)(rowbase + tp1) * ZS + 2816 + ch]);
;       const float z3 = bf2f(z[(size_t)(rowbase + tp2) * ZS + 2816 + ch]);
;       float xr = w1 * z1;
;       xr += (tp - 1 >= 0 ? w0 : 0.f) * z0;
;       xr += (tp + 1 < L ? w2 : 0.f) * z2;
;       xr += (tp + 2 < L ? w3 : 0.f) * z3;
;       XR[tt * 65 + i] = xr;
;       XB[tt * 72 + i] = f2bf(xr);
;     }
;     const bf16_t* rgw = (const bf16_t*)(p.ws + OFF_RGW);
; #pragma unroll
;     for (int q = 0; q < 4; ++q) {
;       const int id = tid + 512 * q;
;       const int row = id >> 3, kc = id & 7;
;       *(uint4*)(WT + row * 72 + kc * 8) = *(const uint4*)(rgw + ((size_t)((l * 4 + (row >> 6)) * 4 + hh)) * 4096 + (row & 63) * 64 + kc * 8);
;     }
;   }
;   __syncthreads();
	s_nop 0
	s_nop 0
	s_nop 0
	s_nop 0
	s_nop 0
	v_or_b32_e32 v43, 4, v12
	s_nop 0
	s_movk_i32 s12, 0x104
	s_movk_i32 s11, 0x90
	s_nop 0
	v_or_b32_e32 v44, 5, v12
	v_or_b32_e32 v45, 6, v12
	v_add_u32_e32 v68, s3, v45
	s_nop 0
	v_add_u32_e32 v69, 2, v68
	v_min_i32_e32 v26, s5, v69
	v_or_b32_e32 v46, 7, v12
	v_add_u32_e32 v13, s2, v26
	v_add_u32_e32 v70, s3, v46
	v_mad_i64_i32 v[26:27], s[8:9], v13, s92, v[0:1]
	v_max_i32_e32 v12, 1, v70
	v_add_u32_e32 v12, s6, v12
	v_mad_u64_u32 v[12:13], s[6:7], v12, s92, v[0:1]
	v_lshl_add_u64 v[12:13], v[12:13], 0, v[32:33]
	v_add_u32_e32 v58, s2, v70
	v_add_co_u32_e32 v12, vcc, s10, v12
	v_mad_i64_i32 v[58:59], s[6:7], v58, s92, v[0:1]
	v_addc_co_u32_e32 v13, vcc, 0, v13, vcc
	v_ashrrev_i32_e32 v80, 3, v52
	s_nop 0
	global_load_ushort v78, v[12:13], off offset:1536
	v_readlane_b32 s2, v254, 5
	v_lshlrev_b32_e32 v12, 4, v52
	v_ashrrev_i32_e32 v33, 7, v52
	s_or_b32 s1, s1, s2
	v_and_b32_e32 v26, 0x70, v12
	v_and_b32_e32 v12, -4, v33
	v_add_u32_e32 v12, s1, v12
	v_ashrrev_i32_e32 v13, 31, v12
	v_readlane_b32 s2, v251, 22
	v_lshlrev_b64 v[12:13], 13, v[12:13]
	v_readlane_b32 s3, v251, 23
	v_lshlrev_b32_e32 v14, 7, v80
	v_and_b32_e32 v14, 0x1f80, v14
	v_lshl_add_u64 v[12:13], s[2:3], 0, v[12:13]
	v_mov_b32_e32 v15, v193
	v_lshl_add_u64 v[12:13], v[12:13], 0, v[14:15]
	v_mov_b32_e32 v27, v193
	v_lshl_add_u64 v[12:13], v[12:13], 0, v[26:27]
	s_nop 0
	global_load_dwordx4 v[12:15], v[12:13], off
	v_add_u32_e32 v0, 0x200, v52
	v_ashrrev_i32_e32 v82, 3, v0
	v_ashrrev_i32_e32 v0, 7, v0
	v_and_b32_e32 v0, -4, v0
	v_add_u32_e32 v0, s1, v0
	v_ashrrev_i32_e32 v1, 31, v0
	v_lshlrev_b64 v[0:1], 13, v[0:1]
	v_lshlrev_b32_e32 v18, 7, v82
	v_lshl_add_u64 v[0:1], s[2:3], 0, v[0:1]
	v_and_b32_e32 v18, 0x1f80, v18
	v_mov_b32_e32 v19, v193
	v_lshl_add_u64 v[0:1], v[0:1], 0, v[18:19]
	v_add_u32_e32 v18, 0x400, v52
	v_ashrrev_i32_e32 v83, 3, v18
	v_ashrrev_i32_e32 v18, 7, v18
	v_and_b32_e32 v18, -4, v18
	v_add_u32_e32 v18, s1, v18
	v_ashrrev_i32_e32 v19, 31, v18
	v_lshlrev_b64 v[18:19], 13, v[18:19]
	v_lshlrev_b32_e32 v20, 7, v83
	v_lshl_add_u64 v[18:19], s[2:3], 0, v[18:19]
	v_and_b32_e32 v20, 0x1f80, v20
	v_mov_b32_e32 v21, v193
	v_lshl_add_u64 v[18:19], v[18:19], 0, v[20:21]
	v_lshl_add_u64 v[0:1], v[0:1], 0, v[26:27]
	v_lshl_add_u64 v[22:23], v[18:19], 0, v[26:27]
	global_load_dwordx4 v[18:21], v[0:1], off
	s_nop 0
	global_load_dwordx4 v[22:25], v[22:23], off
	v_add_u32_e32 v0, 0x600, v52
	v_ashrrev_i32_e32 v84, 3, v0
	v_ashrrev_i32_e32 v0, 7, v0
	v_and_b32_e32 v0, -4, v0
	v_add_u32_e32 v0, s1, v0
	v_ashrrev_i32_e32 v1, 31, v0
	v_lshlrev_b64 v[0:1], 13, v[0:1]
	v_lshlrev_b32_e32 v58, 7, v84
	v_lshl_add_u64 v[0:1], s[2:3], 0, v[0:1]
	v_and_b32_e32 v58, 0x1f80, v58
	v_mov_b32_e32 v59, v193
	v_lshl_add_u64 v[0:1], v[0:1], 0, v[58:59]
	v_lshl_add_u64 v[0:1], v[0:1], 0, v[26:27]
	global_load_dwordx4 v[58:61], v[0:1], off
	s_waitcnt vmcnt(0)
	v_lshlrev_b32_e32 v1, 16, v78
	s_nop 0
	s_nop 0
	v_add_u32_e32 v0, 0, v26
	v_mad_u64_u32 v[2:3], s[0:1], v80, s11, v[0:1]
	ds_write_b128 v2, v[12:15] offset:25856
	v_mad_u64_u32 v[2:3], s[0:1], v82, s11, v[0:1]
	ds_write_b128 v2, v[18:21] offset:25856
	v_mad_u64_u32 v[2:3], s[0:1], v83, s11, v[0:1]
	v_mad_u64_u32 v[0:1], s[0:1], v84, s11, v[0:1]
	ds_write_b128 v2, v[22:25] offset:25856
	ds_write_b128 v0, v[58:61] offset:25856
	v_and_b32_e32 v0, 48, v52
	v_add_u32_e32 v0, 0, v0
	v_mad_u32_u24 v17, v6, s11, v0
	s_waitcnt vmcnt(0)
	v_lshlrev_b32_e32 v154, 16, v154
	v_lshlrev_b32_e32 v155, 16, v155
	v_lshlrev_b32_e32 v156, 16, v156
	v_lshlrev_b32_e32 v157, 16, v157
	v_lshlrev_b32_e32 v158, 16, v158
	v_lshlrev_b32_e32 v159, 16, v159
	v_lshlrev_b32_e32 v160, 16, v160
	v_lshlrev_b32_e32 v161, 16, v161
	v_lshlrev_b32_e32 v162, 16, v162
	v_lshlrev_b32_e32 v163, 16, v163
	v_lshlrev_b32_e32 v164, 16, v164
	s_cmp_ge_i32 s45, 1
	s_cselect_b64 s[56:57], -1, 0
	s_add_i32 s55, s45, 8
	s_cmp_lt_i32 s55, s47
	s_cselect_b64 s[58:59], -1, 0
	v_cndmask_b32_e64 v169, 0, v165, s[56:57]
	v_cndmask_b32_e64 v170, 0, v167, s[58:59]
	v_cndmask_b32_e64 v171, 0, v168, s[58:59]
	v_mul_f32_e32 v172, v166, v155
	v_fmac_f32_e32 v172, v169, v154
	v_fmac_f32_e32 v172, v167, v156
	v_fmac_f32_e32 v172, v168, v157
	v_mul_f32_e32 v173, v166, v156
	v_fmac_f32_e32 v173, v165, v155
	v_fmac_f32_e32 v173, v167, v157
	v_fmac_f32_e32 v173, v168, v158
	v_mul_f32_e32 v174, v166, v157
	v_fmac_f32_e32 v174, v165, v156
	v_fmac_f32_e32 v174, v167, v158
	v_fmac_f32_e32 v174, v168, v159
	v_mul_f32_e32 v175, v166, v158
	v_fmac_f32_e32 v175, v165, v157
	v_fmac_f32_e32 v175, v167, v159
	v_fmac_f32_e32 v175, v168, v160
	v_mul_f32_e32 v176, v166, v159
	v_fmac_f32_e32 v176, v165, v158
	v_fmac_f32_e32 v176, v167, v160
	v_fmac_f32_e32 v176, v168, v161
	v_mul_f32_e32 v177, v166, v160
	v_fmac_f32_e32 v177, v165, v159
	v_fmac_f32_e32 v177, v167, v161
	v_fmac_f32_e32 v177, v168, v162
	v_mul_f32_e32 v178, v166, v161
	v_fmac_f32_e32 v178, v165, v160
	v_fmac_f32_e32 v178, v167, v162
	v_fmac_f32_e32 v178, v171, v163
	v_mul_f32_e32 v179, v166, v162
	v_fmac_f32_e32 v179, v165, v161
	v_fmac_f32_e32 v179, v170, v163
	v_fmac_f32_e32 v179, v171, v164
	v_cvt_pk_bf16_f32 v184, v172, v172
	ds_write_b32 v182, v172
	ds_write_b16 v183, v184 offset:16640
	v_cvt_pk_bf16_f32 v184, v173, v173
	ds_write_b32 v182, v173 offset:260
	ds_write_b16 v183, v184 offset:16784
	v_cvt_pk_bf16_f32 v184, v174, v174
	ds_write_b32 v182, v174 offset:520
	ds_write_b16 v183, v184 offset:16928
	v_cvt_pk_bf16_f32 v184, v175, v175
	ds_write_b32 v182, v175 offset:780
	ds_write_b16 v183, v184 offset:17072
	v_cvt_pk_bf16_f32 v184, v176, v176
	ds_write_b32 v182, v176 offset:1040
	ds_write_b16 v183, v184 offset:17216
	v_cvt_pk_bf16_f32 v184, v177, v177
	ds_write_b32 v182, v177 offset:1300
	ds_write_b16 v183, v184 offset:17360
	v_cvt_pk_bf16_f32 v184, v178, v178
	ds_write_b32 v182, v178 offset:1560
	ds_write_b16 v183, v184 offset:17504
	v_cvt_pk_bf16_f32 v184, v179, v179
	ds_write_b32 v182, v179 offset:1820
	ds_write_b16 v183, v184 offset:17648
	s_waitcnt lgkmcnt(0)
	s_barrier
; __device__ __forceinline__ float fexp(float x) { return __expf(x); }
; __device__ __forceinline__ float sigm(float x) { return frcp(1.f + fexp(-x)); }
; __device__ __forceinline__ float softplusf(float x) { return fmaxf(x, 0.f) + __logf(1.f + fexp(-fabsf(x))); }
; __device__ void rg_tile(unsigned char* lds, const Params& p, int l, int b, int ck, int hh, bool outmode) {
;     ...
;   {
;     const int d = w >> 2, jf = w & 3;
;     f32x4 ar[4], ai[4];
; #pragma unroll
;     for (int i = 0; i < 4; ++i) { ar[i] = (f32x4){0.f, 0.f, 0.f, 0.f}; ai[i] = (f32x4){0.f, 0.f, 0.f, 0.f}; }
; #pragma unroll
;     for (int ks = 0; ks < 2; ++ks) {
;       const bf16x8 wr = ldfrag(WT + ((d * 2 + 0) * 64 + jf * 16 + lr) * 72 + ks * 32 + lg * 8);
;       const bf16x8 wi = ldfrag(WT + ((d * 2 + 1) * 64 + jf * 16 + lr) * 72 + ks * 32 + lg * 8);
; #pragma unroll
;       for (int tf = 0; tf < 4; ++tf) {
;         const bf16x8 xf = ldfrag(XB + (tf * 16 + lr) * 72 + ks * 32 + lg * 8);
;         ar[tf] = mfma16(xf, wr, ar[tf]);
;         ai[tf] = mfma16(xf, wi, ai[tf]);
;       }
;     }
;     const int j = jf * 16 + lr;
;     const int ch = hh * 64 + j;
;     const float sp = softplusf(-lam_);
; #pragma unroll
;     for (int tf = 0; tf < 4; ++tf)
; #pragma unroll
;       for (int jj = 0; jj < 4; ++jj) {
;         const int tt = tf * 16 + lg * 4 + jj;
;         const float r = sigm(ar[tf][jj] + br);
;         const float ig = sigm(ai[tf][jj] + bi);
;         const float la = -8.0f * r * sp;
;         const float a = fexp(la);
;         const float bq = __builtin_amdgcn_sqrtf(fmaxf(1.f - a * a, 0.f)) * ig * XR[tt * 65 + j];
;         AA[(d * 64 + tt) * 64 + j] = a;
;         BQ[(d * 64 + tt) * 64 + j] = bq;
;       }
;   }
	ds_read_b128 v[18:21], v17 offset:16640
	v_lshl_or_b32 v1, v56, 7, v55
	v_mad_u64_u32 v[2:3], s[0:1], v1, s11, v[0:1]
	v_lshl_or_b32 v1, v7, 6, v55
	ds_read_b128 v[12:15], v2 offset:25856
	v_mad_u64_u32 v[0:1], s[0:1], v1, s11, v[0:1]
	ds_read_b128 v[4:7], v2 offset:25920
	ds_read_b128 v[22:25], v17 offset:16704
	ds_read_b128 v[8:11], v0 offset:25856
	ds_read_b128 v[0:3], v0 offset:25920
	s_mov_b32 s0, 0xbfb8aa3b
	v_mul_f32_e64 v26, |v16|, s0
	s_waitcnt lgkmcnt(4)
	v_mfma_f32_16x16x32_bf16 v[58:61], v[18:21], v[12:15], 0
	v_exp_f32_e32 v26, v26
	s_mov_b32 s0, 0x800000
	v_max_f32_e64 v16, -v16, -v16
	s_waitcnt lgkmcnt(1)
	v_mfma_f32_16x16x32_bf16 v[18:21], v[18:21], v[8:11], 0
	v_max_f32_e32 v16, 0, v16
	v_bfe_u32 v82, v52, 4, 2
	ds_read_b128 v[62:65], v17 offset:18944
	ds_read_b128 v[66:69], v17 offset:19008
	s_waitcnt lgkmcnt(2)
	v_mfma_f32_16x16x32_bf16 v[74:77], v[22:25], v[0:3], v[18:21]
	v_lshlrev_b32_e32 v56, 12, v56
	v_and_b32_e32 v52, 0x1fffff80, v52
	s_nop 0
	v_add_f32_e32 v18, 1.0, v26
	v_cmp_gt_f32_e32 vcc, s0, v18
	v_mfma_f32_16x16x32_bf16 v[58:61], v[22:25], v[4:7], v[58:61]
	s_mov_b32 s0, 0x3f317217
	v_cndmask_b32_e64 v19, 0, 32, vcc
	v_ldexp_f32 v18, v18, v19
	v_log_f32_e32 v18, v18
	v_mov_b32_e32 v20, 0x41b17218
	v_cndmask_b32_e32 v20, 0, v20, vcc
	s_nop 1
	v_add_f32_e32 v59, v54, v59
	v_mul_f32_e32 v19, 0x3f317217, v18
	v_fma_f32 v19, v18, s0, -v19
	v_fmac_f32_e32 v19, 0x3377d1cf, v18
	s_mov_b32 s0, 0x7f800000
	v_fmac_f32_e32 v19, 0x3f317217, v18
	v_cmp_lt_f32_e64 s[0:1], |v18|, s0
	ds_read_b128 v[78:81], v17 offset:21248
	ds_read_b128 v[24:27], v17 offset:21312
	v_cndmask_b32_e64 v18, v18, v19, s[0:1]
	v_add_f32_e32 v19, v54, v58
	v_mul_f32_e32 v19, 0xbfb8aa3b, v19
	v_exp_f32_e32 v19, v19
	v_sub_f32_e32 v18, v18, v20
	v_add_f32_e32 v57, v16, v18
	v_add_f32_e32 v18, v53, v74
	v_add_f32_e32 v16, 1.0, v19
	v_rcp_f32_e32 v16, v16
	v_mul_f32_e32 v18, 0xbfb8aa3b, v18
	v_exp_f32_e32 v18, v18
	v_lshl_add_u32 v74, v55, 2, 0
	v_mul_f32_e32 v16, 0xc1000000, v16
	v_mul_f32_e32 v16, v57, v16
	v_mul_f32_e32 v16, 0x3fb8aa3b, v16
	v_exp_f32_e32 v58, v16
	v_add_f32_e32 v16, 1.0, v18
	v_rcp_f32_e32 v83, v16
	s_movk_i32 s0, 0x410
	v_fma_f32 v16, -v58, v58, 1.0
	v_max_f32_e32 v16, 0, v16
	v_sqrt_f32_e32 v84, v16
	v_mad_u32_u24 v16, v82, s0, v74
	ds_read_b32 v85, v16
	ds_read_b128 v[20:23], v17 offset:23552
	ds_read_b128 v[16:19], v17 offset:23616
	v_mul_f32_e32 v59, 0xbfb8aa3b, v59
	v_mul_f32_e32 v83, v83, v84
	v_lshlrev_b32_e32 v84, 8, v82
	v_or3_b32 v84, v84, v56, v55
	v_exp_f32_e32 v59, v59
	v_lshlrev_b32_e32 v84, 2, v84
	s_waitcnt lgkmcnt(2)
	v_mul_f32_e32 v83, v85, v83
	v_add_u32_e32 v85, 0, v84
	v_readlane_b32 s0, v253, 37
	ds_write_b32 v85, v58 offset:62720
	v_mfma_f32_16x16x32_bf16 v[70:73], v[62:65], v[12:15], 0
	v_add_u32_e32 v58, s0, v84
	ds_write_b32 v58, v83
	v_add_f32_e32 v58, 1.0, v59
	v_add_f32_e32 v59, v53, v75
	v_lshl_or_b32 v75, v82, 2, 1
	v_rcp_f32_e32 v58, v58
	v_mad_u32_u24 v74, v75, s12, v74
	v_lshlrev_b32_e32 v75, 6, v75
	v_or3_b32 v55, v75, v56, v55
	v_add_f32_e32 v56, v54, v60
	v_mul_f32_e32 v56, 0xbfb8aa3b, v56
	v_exp_f32_e32 v56, v56
	v_mul_f32_e32 v58, 0xc1000000, v58
	v_mul_f32_e32 v58, v57, v58
	v_mul_f32_e32 v58, 0x3fb8aa3b, v58
	v_mul_f32_e32 v59, 0xbfb8aa3b, v59
	v_exp_f32_e32 v58, v58
	v_add_f32_e32 v56, 1.0, v56
	v_exp_f32_e32 v59, v59
	v_rcp_f32_e32 v56, v56
	v_fma_f32 v82, -v58, v58, 1.0
	v_lshlrev_b32_e32 v55, 2, v55
	v_add_f32_e32 v59, 1.0, v59
	v_max_f32_e32 v82, 0, v82
	v_add_u32_e32 v60, 0, v55
	v_mul_f32_e32 v56, 0xc1000000, v56
	v_rcp_f32_e32 v59, v59
	v_sqrt_f32_e32 v82, v82
	ds_read_b32 v83, v74
	ds_write_b32 v60, v58 offset:62720
	v_add_f32_e32 v58, v53, v76
	v_mul_f32_e32 v56, v57, v56
	v_mul_f32_e32 v58, 0xbfb8aa3b, v58
	v_mul_f32_e32 v56, 0x3fb8aa3b, v56
	v_exp_f32_e32 v58, v58
	v_exp_f32_e32 v56, v56
	v_mul_f32_e32 v59, v59, v82
	s_waitcnt lgkmcnt(1)
	v_mul_f32_e32 v59, v83, v59
	v_add_u32_e32 v55, s0, v55
	ds_write_b32 v55, v59
	v_add_f32_e32 v55, 1.0, v58
	v_fma_f32 v58, -v56, v56, 1.0
	v_max_f32_e32 v58, 0, v58
	v_rcp_f32_e32 v55, v55
	v_sqrt_f32_e32 v58, v58
	ds_read_b32 v59, v74 offset:260
	v_mfma_f32_16x16x32_bf16 v[62:65], v[62:65], v[8:11], 0
	v_cmp_eq_u32_e32 vcc, 0, v48
	v_mul_f32_e32 v55, v55, v58
	v_or_b32_e32 v58, 0x200, v84
	s_waitcnt lgkmcnt(0)
	v_mul_f32_e32 v55, v55, v59
	v_add_f32_e32 v59, v54, v61
	v_mul_f32_e32 v59, 0xbfb8aa3b, v59
	v_exp_f32_e32 v59, v59
	v_add_u32_e32 v60, 0, v58
	ds_write_b32 v60, v56 offset:62720
	v_add_u32_e32 v56, s0, v58
	v_add_f32_e32 v58, 1.0, v59
	v_rcp_f32_e32 v58, v58
	v_add_f32_e32 v59, v53, v77
	v_mul_f32_e32 v59, 0xbfb8aa3b, v59
	v_mfma_f32_16x16x32_bf16 v[70:73], v[66:69], v[4:7], v[70:73]
	v_exp_f32_e32 v59, v59
	v_mul_f32_e32 v58, 0xc1000000, v58
	v_mul_f32_e32 v58, v57, v58
	v_mul_f32_e32 v58, 0x3fb8aa3b, v58
	v_exp_f32_e32 v75, v58
	ds_write_b32 v56, v55
	v_add_f32_e32 v55, 1.0, v59
	v_mfma_f32_16x16x32_bf16 v[58:61], v[66:69], v[0:3], v[62:65]
	v_fma_f32 v56, -v75, v75, 1.0
	v_max_f32_e32 v56, 0, v56
	v_rcp_f32_e32 v55, v55
	v_add_f32_e32 v62, v54, v70
	v_mul_f32_e32 v62, 0xbfb8aa3b, v62
	v_exp_f32_e32 v62, v62
	v_sqrt_f32_e32 v56, v56
	ds_read_b32 v76, v74 offset:520
	v_add_f32_e32 v58, v53, v58
	v_add_f32_e32 v62, 1.0, v62
	v_rcp_f32_e32 v62, v62
	v_mul_f32_e32 v58, 0xbfb8aa3b, v58
	v_exp_f32_e32 v58, v58
	v_mul_f32_e32 v55, v55, v56
	v_mul_f32_e32 v62, 0xc1000000, v62
	v_mul_f32_e32 v62, v57, v62
	v_mul_f32_e32 v62, 0x3fb8aa3b, v62
	v_exp_f32_e32 v66, v62
	v_or_b32_e32 v56, 0x300, v84
	s_waitcnt lgkmcnt(0)
; __device__ __forceinline__ float fexp(float x) { return __expf(x); }
; __device__ __forceinline__ float sigm(float x) { return frcp(1.f + fexp(-x)); }
; __device__ void rg_tile(unsigned char* lds, const Params& p, int l, int b, int ck, int hh, bool outmode) {
;     ...
; #pragma unroll
;     for (int tf = 0; tf < 4; ++tf)
; #pragma unroll
;       for (int jj = 0; jj < 4; ++jj) {
;         const int tt = tf * 16 + lg * 4 + jj;
;         const float r = sigm(ar[tf][jj] + br);
;         const float ig = sigm(ai[tf][jj] + bi);
;         const float la = -8.0f * r * sp;
;         const float a = fexp(la);
;         const float bq = __builtin_amdgcn_sqrtf(fmaxf(1.f - a * a, 0.f)) * ig * XR[tt * 65 + j];
;         AA[(d * 64 + tt) * 64 + j] = a;
;         BQ[(d * 64 + tt) * 64 + j] = bq;
;       }
	v_mul_f32_e32 v55, v55, v76
	v_add_u32_e32 v63, 0, v56
	v_add_u32_e32 v56, s0, v56
	ds_write_b32 v56, v55
	v_fma_f32 v56, -v66, v66, 1.0
	ds_write_b32 v63, v75 offset:62720
	v_add_f32_e32 v55, 1.0, v58
	v_max_f32_e32 v56, 0, v56
	v_rcp_f32_e32 v55, v55
	v_sqrt_f32_e32 v56, v56
	ds_read_b32 v58, v74 offset:3900
	v_add_f32_e32 v59, v53, v59
	v_mul_f32_e32 v59, 0xbfb8aa3b, v59
	v_mul_f32_e32 v55, v55, v56
	v_exp_f32_e32 v59, v59
	s_waitcnt lgkmcnt(0)
	v_mul_f32_e32 v55, v55, v58
	v_add_f32_e32 v58, v54, v71
	v_mul_f32_e32 v58, 0xbfb8aa3b, v58
	v_exp_f32_e32 v58, v58
	v_or_b32_e32 v56, 0x1000, v84
	v_add_u32_e32 v67, 0, v56
	v_add_u32_e32 v56, s0, v56
	v_add_f32_e32 v58, 1.0, v58
	v_rcp_f32_e32 v58, v58
	ds_write_b32 v56, v55
	ds_write_b32 v67, v66 offset:62720
	v_add_f32_e32 v55, 1.0, v59
	v_mul_f32_e32 v58, 0xc1000000, v58
	v_mul_f32_e32 v58, v57, v58
	v_mul_f32_e32 v58, 0x3fb8aa3b, v58
	v_exp_f32_e32 v58, v58
	v_rcp_f32_e32 v55, v55
	ds_read_b32 v59, v74 offset:4160
	v_mfma_f32_16x16x32_bf16 v[62:65], v[78:81], v[12:15], 0
	v_fma_f32 v56, -v58, v58, 1.0
	v_max_f32_e32 v56, 0, v56
	v_sqrt_f32_e32 v56, v56
	v_mfma_f32_16x16x32_bf16 v[62:65], v[24:27], v[4:7], v[62:65]
	v_mul_f32_e32 v55, v55, v56
	s_waitcnt lgkmcnt(0)
	v_mul_f32_e32 v55, v55, v59
	v_add_f32_e32 v59, v54, v72
	v_mul_f32_e32 v59, 0xbfb8aa3b, v59
	v_exp_f32_e32 v59, v59
	v_or_b32_e32 v56, 0x1100, v84
	v_add_u32_e32 v70, 0, v56
	ds_write_b32 v70, v58 offset:62720
	v_add_f32_e32 v58, 1.0, v59
	v_rcp_f32_e32 v58, v58
	v_add_f32_e32 v59, v53, v60
	v_mul_f32_e32 v59, 0xbfb8aa3b, v59
	v_exp_f32_e32 v59, v59
	v_mul_f32_e32 v58, 0xc1000000, v58
	v_mul_f32_e32 v58, v57, v58
	v_mul_f32_e32 v58, 0x3fb8aa3b, v58
	v_exp_f32_e32 v58, v58
	v_add_u32_e32 v56, s0, v56
	ds_write_b32 v56, v55
	v_add_f32_e32 v55, 1.0, v59
	v_fma_f32 v56, -v58, v58, 1.0
	v_max_f32_e32 v56, 0, v56
	v_rcp_f32_e32 v55, v55
	v_sqrt_f32_e32 v56, v56
	ds_read_b32 v59, v74 offset:4420
	v_mfma_f32_16x16x32_bf16 v[66:69], v[78:81], v[8:11], 0
	v_mul_f32_e32 v55, v55, v56
	v_or_b32_e32 v56, 0x1200, v84
	s_waitcnt lgkmcnt(0)
	v_mul_f32_e32 v55, v55, v59
	v_add_f32_e32 v59, v54, v73
	v_mul_f32_e32 v59, 0xbfb8aa3b, v59
	v_exp_f32_e32 v59, v59
	v_add_u32_e32 v60, 0, v56
	ds_write_b32 v60, v58 offset:62720
	v_add_u32_e32 v56, s0, v56
	v_add_f32_e32 v58, 1.0, v59
	v_rcp_f32_e32 v58, v58
	v_add_f32_e32 v59, v53, v61
	v_mul_f32_e32 v59, 0xbfb8aa3b, v59
	v_exp_f32_e32 v59, v59
	v_mul_f32_e32 v58, 0xc1000000, v58
	v_mul_f32_e32 v58, v57, v58
	v_mul_f32_e32 v58, 0x3fb8aa3b, v58
	v_exp_f32_e32 v58, v58
	ds_write_b32 v56, v55
	v_add_f32_e32 v55, 1.0, v59
	v_rcp_f32_e32 v55, v55
	v_fma_f32 v56, -v58, v58, 1.0
	v_max_f32_e32 v56, 0, v56
	v_sqrt_f32_e32 v56, v56
	ds_read_b32 v59, v74 offset:4680
	v_mfma_f32_16x16x32_bf16 v[24:27], v[24:27], v[0:3], v[66:69]
	v_mul_f32_e32 v55, v55, v56
	v_or_b32_e32 v56, 0x1300, v84
	s_waitcnt lgkmcnt(0)
	v_mul_f32_e32 v55, v55, v59
	v_add_f32_e32 v59, v54, v62
	v_mul_f32_e32 v59, 0xbfb8aa3b, v59
	v_exp_f32_e32 v59, v59
	v_add_u32_e32 v60, 0, v56
	ds_write_b32 v60, v58 offset:62720
	v_add_f32_e32 v24, v53, v24
	v_add_f32_e32 v58, 1.0, v59
	v_rcp_f32_e32 v58, v58
	v_mul_f32_e32 v24, 0xbfb8aa3b, v24
	v_exp_f32_e32 v24, v24
	v_add_u32_e32 v56, s0, v56
	v_mul_f32_e32 v58, 0xc1000000, v58
	v_mul_f32_e32 v58, v57, v58
	v_mul_f32_e32 v58, 0x3fb8aa3b, v58
	v_exp_f32_e32 v58, v58
	ds_write_b32 v56, v55
	v_add_f32_e32 v24, 1.0, v24
	v_rcp_f32_e32 v24, v24
	v_fma_f32 v55, -v58, v58, 1.0
	v_max_f32_e32 v55, 0, v55
	v_sqrt_f32_e32 v55, v55
	ds_read_b32 v56, v74 offset:8060
	v_mfma_f32_16x16x32_bf16 v[12:15], v[20:23], v[12:15], 0
	v_add_f32_e32 v25, v53, v25
	v_mul_f32_e32 v24, v24, v55
	v_mul_f32_e32 v25, 0xbfb8aa3b, v25
	s_waitcnt lgkmcnt(0)
	v_mul_f32_e32 v24, v24, v56
	v_add_f32_e32 v56, v54, v63
	v_mul_f32_e32 v56, 0xbfb8aa3b, v56
	v_exp_f32_e32 v56, v56
	v_mfma_f32_16x16x32_bf16 v[8:11], v[20:23], v[8:11], 0
	v_add_f32_e32 v22, v54, v64
	v_mul_f32_e32 v22, 0xbfb8aa3b, v22
	v_add_f32_e32 v56, 1.0, v56
	v_rcp_f32_e32 v56, v56
	v_exp_f32_e32 v22, v22
	v_exp_f32_e32 v25, v25
	v_or_b32_e32 v55, 0x2000, v84
	v_mul_f32_e32 v56, 0xc1000000, v56
	v_mul_f32_e32 v56, v57, v56
	v_mul_f32_e32 v56, 0x3fb8aa3b, v56
	v_exp_f32_e32 v56, v56
	v_add_f32_e32 v22, 1.0, v22
	v_rcp_f32_e32 v22, v22
	v_mfma_f32_16x16x32_bf16 v[4:7], v[16:19], v[4:7], v[12:15]
	v_add_u32_e32 v59, 0, v55
	v_add_u32_e32 v55, s0, v55
	ds_write_b32 v55, v24
	v_add_f32_e32 v14, v54, v65
	v_mul_f32_e32 v14, 0xbfb8aa3b, v14
	v_add_f32_e32 v24, 1.0, v25
	v_fma_f32 v25, -v56, v56, 1.0
	v_exp_f32_e32 v14, v14
	ds_write_b32 v59, v58 offset:62720
	v_max_f32_e32 v25, 0, v25
	v_or_b32_e32 v21, 0x2100, v84
	v_mul_f32_e32 v22, 0xc1000000, v22
	v_rcp_f32_e32 v24, v24
	v_sqrt_f32_e32 v25, v25
	ds_read_b32 v55, v74 offset:8320
	v_add_u32_e32 v23, 0, v21
	v_mul_f32_e32 v22, v57, v22
	ds_write_b32 v23, v56 offset:62720
	v_add_f32_e32 v23, v53, v26
	v_mul_f32_e32 v22, 0x3fb8aa3b, v22
	v_mul_f32_e32 v23, 0xbfb8aa3b, v23
	v_exp_f32_e32 v22, v22
	v_add_f32_e32 v14, 1.0, v14
	v_exp_f32_e32 v23, v23
	v_rcp_f32_e32 v14, v14
	v_mul_f32_e32 v20, v24, v25
	v_add_f32_e32 v4, v54, v4
	s_waitcnt lgkmcnt(1)
	v_mul_f32_e32 v20, v20, v55
	v_add_u32_e32 v21, s0, v21
	v_mul_f32_e32 v4, 0xbfb8aa3b, v4
	ds_write_b32 v21, v20
	v_fma_f32 v21, -v22, v22, 1.0
	v_exp_f32_e32 v4, v4
	v_add_f32_e32 v20, 1.0, v23
	v_max_f32_e32 v21, 0, v21
	v_or_b32_e32 v13, 0x2200, v84
	v_mul_f32_e32 v14, 0xc1000000, v14
	v_rcp_f32_e32 v20, v20
	v_sqrt_f32_e32 v21, v21
	ds_read_b32 v23, v74 offset:8580
	v_add_u32_e32 v15, 0, v13
	v_mul_f32_e32 v14, v57, v14
	ds_write_b32 v15, v22 offset:62720
	v_add_f32_e32 v15, v53, v27
	v_mul_f32_e32 v14, 0x3fb8aa3b, v14
	v_mul_f32_e32 v15, 0xbfb8aa3b, v15
	v_exp_f32_e32 v14, v14
	v_add_f32_e32 v4, 1.0, v4
	v_exp_f32_e32 v15, v15
	v_rcp_f32_e32 v4, v4
	v_mul_f32_e32 v12, v20, v21
	s_waitcnt lgkmcnt(1)
; __device__ __forceinline__ float fexp(float x) { return __expf(x); }
; __device__ __forceinline__ float sigm(float x) { return frcp(1.f + fexp(-x)); }
; __device__ void rg_tile(unsigned char* lds, const Params& p, int l, int b, int ck, int hh, bool outmode) {
;     ...
; #pragma unroll
;     for (int tf = 0; tf < 4; ++tf)
; #pragma unroll
;       for (int jj = 0; jj < 4; ++jj) {
;         const int tt = tf * 16 + lg * 4 + jj;
;         const float r = sigm(ar[tf][jj] + br);
;         const float ig = sigm(ai[tf][jj] + bi);
;         const float la = -8.0f * r * sp;
;         const float a = fexp(la);
;         const float bq = __builtin_amdgcn_sqrtf(fmaxf(1.f - a * a, 0.f)) * ig * XR[tt * 65 + j];
;         AA[(d * 64 + tt) * 64 + j] = a;
;         BQ[(d * 64 + tt) * 64 + j] = bq;
;       }
;   }
;   __syncthreads();
;   {
;     float* SEG = XR;
;     const int seg = tid >> 7, d = (tid >> 6) & 1, j = tid & 63;
;     const int ch = hh * 64 + j;
;     const size_t ci = ((size_t)(b * 36 + ck) * 2 + d) * 256 + ch;
;     float H = 0.f, Ap = 1.f;
; #pragma unroll
;     for (int q = 0; q < 16; ++q) {
;       const int pos = seg * 16 + q;
;       const int tt = d == 0 ? pos : 63 - pos;
;       const float a = AA[(d * 64 + tt) * 64 + j];
	v_mul_f32_e32 v12, v12, v23
	v_add_u32_e32 v13, s0, v13
	v_mfma_f32_16x16x32_bf16 v[0:3], v[16:19], v[0:3], v[8:11]
	v_add_f32_e32 v5, v54, v5
	ds_write_b32 v13, v12
	v_fma_f32 v13, -v14, v14, 1.0
	v_mul_f32_e32 v5, 0xbfb8aa3b, v5
	v_add_f32_e32 v12, 1.0, v15
	v_max_f32_e32 v13, 0, v13
	v_mul_f32_e32 v4, 0xc1000000, v4
	v_exp_f32_e32 v5, v5
	v_rcp_f32_e32 v12, v12
	v_sqrt_f32_e32 v13, v13
	ds_read_b32 v15, v74 offset:8840
	v_mul_f32_e32 v4, v57, v4
	v_add_f32_e32 v0, v53, v0
	v_mul_f32_e32 v4, 0x3fb8aa3b, v4
	v_mul_f32_e32 v0, 0xbfb8aa3b, v0
	v_exp_f32_e32 v4, v4
	v_exp_f32_e32 v0, v0
	v_add_f32_e32 v5, 1.0, v5
	v_mul_f32_e32 v8, v12, v13
	v_or_b32_e32 v9, 0x2300, v84
	v_rcp_f32_e32 v5, v5
	s_waitcnt lgkmcnt(0)
	v_mul_f32_e32 v8, v8, v15
	v_add_u32_e32 v10, 0, v9
	v_add_u32_e32 v9, s0, v9
	ds_write_b32 v9, v8
	v_fma_f32 v8, -v4, v4, 1.0
	ds_write_b32 v10, v14 offset:62720
	v_add_f32_e32 v0, 1.0, v0
	v_max_f32_e32 v8, 0, v8
	v_rcp_f32_e32 v0, v0
	v_sqrt_f32_e32 v8, v8
	ds_read_b32 v9, v74 offset:12220
	v_mul_f32_e32 v5, 0xc1000000, v5
	v_add_f32_e32 v1, v53, v1
	v_mul_f32_e32 v5, v57, v5
	v_mul_f32_e32 v1, 0xbfb8aa3b, v1
	v_mul_f32_e32 v5, 0x3fb8aa3b, v5
	v_exp_f32_e32 v1, v1
	v_exp_f32_e32 v5, v5
	v_mul_f32_e32 v0, v0, v8
	v_or_b32_e32 v8, 0x3000, v84
	s_waitcnt lgkmcnt(0)
	v_mul_f32_e32 v0, v0, v9
	v_add_u32_e32 v9, 0, v8
	ds_write_b32 v9, v4 offset:62720
	v_add_u32_e32 v4, s0, v8
	ds_write_b32 v4, v0
	v_add_f32_e32 v0, 1.0, v1
	v_fma_f32 v1, -v5, v5, 1.0
	v_max_f32_e32 v1, 0, v1
	v_rcp_f32_e32 v0, v0
	v_sqrt_f32_e32 v1, v1
	ds_read_b32 v4, v74 offset:12480
	v_add_f32_e32 v2, v53, v2
	v_mul_f32_e32 v2, 0xbfb8aa3b, v2
	v_mul_f32_e32 v0, v0, v1
	v_exp_f32_e32 v2, v2
	s_waitcnt lgkmcnt(0)
	v_mul_f32_e32 v0, v0, v4
	v_add_f32_e32 v4, v54, v6
	v_mul_f32_e32 v4, 0xbfb8aa3b, v4
	v_exp_f32_e32 v4, v4
	v_or_b32_e32 v1, 0x3100, v84
	v_add_u32_e32 v6, 0, v1
	v_add_u32_e32 v1, s0, v1
	v_add_f32_e32 v4, 1.0, v4
	v_rcp_f32_e32 v4, v4
	ds_write_b32 v1, v0
	ds_write_b32 v6, v5 offset:62720
	v_add_f32_e32 v0, 1.0, v2
	v_mul_f32_e32 v4, 0xc1000000, v4
	v_mul_f32_e32 v4, v57, v4
	v_mul_f32_e32 v4, 0x3fb8aa3b, v4
	v_exp_f32_e32 v4, v4
	v_rcp_f32_e32 v0, v0
	ds_read_b32 v2, v74 offset:12740
	v_add_f32_e32 v3, v53, v3
	v_fma_f32 v1, -v4, v4, 1.0
	v_max_f32_e32 v1, 0, v1
	v_sqrt_f32_e32 v1, v1
	v_mul_f32_e32 v3, 0xbfb8aa3b, v3
	v_exp_f32_e32 v3, v3
	v_lshlrev_b32_e32 v20, 4, v33
	v_mul_f32_e32 v0, v0, v1
	s_waitcnt lgkmcnt(0)
	v_mul_f32_e32 v0, v0, v2
	v_add_f32_e32 v2, v54, v7
	v_mul_f32_e32 v2, 0xbfb8aa3b, v2
	v_exp_f32_e32 v2, v2
	v_or_b32_e32 v1, 0x3200, v84
	v_add_u32_e32 v5, 0, v1
	v_add_u32_e32 v1, s0, v1
	v_add_f32_e32 v2, 1.0, v2
	v_rcp_f32_e32 v2, v2
	ds_write_b32 v1, v0
	ds_write_b32 v5, v4 offset:62720
	v_add_f32_e32 v0, 1.0, v3
	v_mul_f32_e32 v2, 0xc1000000, v2
	v_mul_f32_e32 v2, v57, v2
	v_mul_f32_e32 v2, 0x3fb8aa3b, v2
	v_exp_f32_e32 v2, v2
	v_rcp_f32_e32 v0, v0
	ds_read_b32 v3, v74 offset:13000
	v_lshl_or_b32 v57, v48, 12, v29
	v_fma_f32 v1, -v2, v2, 1.0
	v_max_f32_e32 v1, 0, v1
	v_sqrt_f32_e32 v1, v1
	v_or_b32_e32 v8, 11, v20
	v_sub_u32_e32 v9, 63, v8
	v_cndmask_b32_e32 v8, v9, v8, vcc
	v_mul_f32_e32 v0, v0, v1
	v_or_b32_e32 v1, 0x3300, v84
	s_waitcnt lgkmcnt(0)
	v_mul_f32_e32 v0, v0, v3
	v_add_u32_e32 v3, 0, v1
	ds_write_b32 v3, v2 offset:62720
	v_or_b32_e32 v2, 1, v20
	v_sub_u32_e32 v3, 63, v2
	v_cndmask_b32_e32 v2, v3, v2, vcc
	v_lshlrev_b32_e32 v2, 6, v2
	v_add_lshl_u32 v2, v2, v57, 2
	v_add_u32_e32 v16, 0, v2
	v_add_u32_e32 v22, s0, v2
	v_or_b32_e32 v2, 2, v20
	v_sub_u32_e32 v3, 63, v2
	v_cndmask_b32_e32 v2, v3, v2, vcc
	v_lshlrev_b32_e32 v2, 6, v2
	v_add_u32_e32 v1, s0, v1
	v_add_lshl_u32 v2, v2, v57, 2
	ds_write_b32 v1, v0
	v_sub_u32_e32 v0, 63, v20
	v_add_u32_e32 v23, 0, v2
	v_add_u32_e32 v24, s0, v2
	v_or_b32_e32 v2, 3, v20
	v_cndmask_b32_e32 v0, v0, v20, vcc
	v_sub_u32_e32 v3, 63, v2
	v_lshlrev_b32_e32 v0, 6, v0
	v_cndmask_b32_e32 v2, v3, v2, vcc
	v_add_lshl_u32 v1, v0, v57, 2
	v_lshlrev_b32_e32 v2, 6, v2
	v_add_u32_e32 v0, 0, v1
	v_add_lshl_u32 v2, v2, v57, 2
	s_waitcnt lgkmcnt(0)
	s_barrier
; __device__ void rg_tile(unsigned char* lds, const Params& p, int l, int b, int ck, int hh, bool outmode) {
;     ...
;   {
;     float* SEG = XR;
;     const int seg = tid >> 7, d = (tid >> 6) & 1, j = tid & 63;
;     const int ch = hh * 64 + j;
;     const size_t ci = ((size_t)(b * 36 + ck) * 2 + d) * 256 + ch;
;     float H = 0.f, Ap = 1.f;
; #pragma unroll
;     for (int q = 0; q < 16; ++q) {
;       const int pos = seg * 16 + q;
;       const int tt = d == 0 ? pos : 63 - pos;
;       const float a = AA[(d * 64 + tt) * 64 + j];
;       H = a * H + BQ[(d * 64 + tt) * 64 + j];
;       Ap *= a;
;     }
;     SEG[((seg * 2 + d) * 64 + j) * 2 + 0] = Ap;
;     SEG[((seg * 2 + d) * 64 + j) * 2 + 1] = H;
;     __syncthreads();
;     ...
;       float hc = car_pre;
;       for (int sgi = 0; sgi < seg; ++sgi) {
;         const float as = SEG[((sgi * 2 + d) * 64 + j) * 2 + 0], hs = SEG[((sgi * 2 + d) * 64 + j) * 2 + 1];
;         hc = as * hc + hs;
;       }
	v_add_u32_e32 v1, s0, v1
	v_add_u32_e32 v25, 0, v2
	v_add_u32_e32 v26, s0, v2
	ds_read_b32 v2, v0 offset:62720
	ds_read_b32 v3, v1
	ds_read_b32 v4, v16 offset:62720
	ds_read_b32 v5, v22
	ds_read_b32 v58, v23 offset:62720
	ds_read_b32 v6, v24
	ds_read_b32 v12, v25 offset:62720
	ds_read_b32 v7, v26
	s_waitcnt lgkmcnt(6)
	v_fmac_f32_e32 v3, 0, v2
	s_waitcnt lgkmcnt(5)
	v_mul_f32_e32 v14, v2, v4
	v_or_b32_e32 v2, 4, v20
	s_waitcnt lgkmcnt(4)
	v_fmac_f32_e32 v5, v3, v4
	v_sub_u32_e32 v3, 63, v2
	v_cndmask_b32_e32 v2, v3, v2, vcc
	v_lshlrev_b32_e32 v2, 6, v2
	v_add_lshl_u32 v2, v2, v57, 2
	v_add_u32_e32 v27, 0, v2
	v_add_u32_e32 v53, s0, v2
	v_or_b32_e32 v2, 5, v20
	v_sub_u32_e32 v3, 63, v2
	v_cndmask_b32_e32 v2, v3, v2, vcc
	v_lshlrev_b32_e32 v2, 6, v2
	v_add_lshl_u32 v2, v2, v57, 2
	v_add_u32_e32 v54, 0, v2
	v_add_u32_e32 v55, s0, v2
	v_or_b32_e32 v2, 6, v20
	v_sub_u32_e32 v3, 63, v2
	v_cndmask_b32_e32 v2, v3, v2, vcc
	v_lshlrev_b32_e32 v2, 6, v2
	v_add_lshl_u32 v3, v2, v57, 2
	v_add_u32_e32 v2, 0, v3
	v_add_u32_e32 v56, s0, v3
	v_or_b32_e32 v3, 7, v20
	v_sub_u32_e32 v4, 63, v3
	v_cndmask_b32_e32 v3, v4, v3, vcc
	v_lshlrev_b32_e32 v3, 6, v3
	s_waitcnt lgkmcnt(2)
	v_fmac_f32_e32 v6, v5, v58
	v_add_lshl_u32 v3, v3, v57, 2
	v_add_u32_e32 v17, 0, v3
	v_add_u32_e32 v10, s0, v3
	ds_read_b32 v60, v27 offset:62720
	ds_read_b32 v3, v53
	ds_read_b32 v18, v54 offset:62720
	ds_read_b32 v4, v55
	ds_read_b32 v62, v2 offset:62720
	ds_read_b32 v5, v56
	ds_read_b32 v64, v17 offset:62720
	ds_read_b32 v11, v10
	s_waitcnt lgkmcnt(8)
	v_fmac_f32_e32 v7, v6, v12
	s_waitcnt lgkmcnt(6)
	v_fmac_f32_e32 v3, v7, v60
	s_waitcnt lgkmcnt(4)
	v_fmac_f32_e32 v4, v3, v18
	v_or_b32_e32 v3, 8, v20
	s_waitcnt lgkmcnt(2)
	v_fmac_f32_e32 v5, v4, v62
	v_sub_u32_e32 v4, 63, v3
	v_cndmask_b32_e32 v3, v4, v3, vcc
	v_lshlrev_b32_e32 v3, 6, v3
	v_add_lshl_u32 v4, v3, v57, 2
	v_add_u32_e32 v3, 0, v4
	v_add_u32_e32 v21, s0, v4
	v_or_b32_e32 v4, 9, v20
	s_waitcnt lgkmcnt(0)
	v_fmac_f32_e32 v11, v5, v64
	v_sub_u32_e32 v5, 63, v4
	v_cndmask_b32_e32 v4, v5, v4, vcc
	v_lshlrev_b32_e32 v4, 6, v4
	v_add_lshl_u32 v5, v4, v57, 2
	v_add_u32_e32 v4, 0, v5
	v_add_u32_e32 v6, s0, v5
	v_or_b32_e32 v5, 10, v20
	v_sub_u32_e32 v7, 63, v5
	v_cndmask_b32_e32 v5, v7, v5, vcc
	v_lshlrev_b32_e32 v5, 6, v5
	v_lshlrev_b32_e32 v8, 6, v8
	v_add_lshl_u32 v7, v5, v57, 2
	v_add_lshl_u32 v9, v8, v57, 2
	v_add_u32_e32 v5, 0, v7
	v_add_u32_e32 v7, s0, v7
	v_add_u32_e32 v8, 0, v9
	v_add_u32_e32 v9, s0, v9
	ds_read_b32 v66, v3 offset:62720
	ds_read_b32 v15, v21
	ds_read_b32 v59, v4 offset:62720
	ds_read_b32 v13, v6
	ds_read_b32 v61, v5 offset:62720
	ds_read_b32 v19, v7
	ds_read_b32 v63, v8 offset:62720
	ds_read_b32 v65, v9
	s_waitcnt lgkmcnt(6)
	v_fmac_f32_e32 v15, v11, v66
	v_mul_f32_e32 v11, v14, v58
	v_mul_f32_e32 v68, v11, v12
	s_waitcnt lgkmcnt(4)
	v_pk_fma_f32 v[12:13], v[14:15], v[58:59], v[12:13]
	v_or_b32_e32 v11, 12, v20
	v_mov_b32_e32 v69, v13
	s_waitcnt lgkmcnt(3)
	v_pk_mul_f32 v[12:13], v[68:69], v[60:61]
	s_waitcnt lgkmcnt(2)
	v_pk_fma_f32 v[68:69], v[68:69], v[60:61], v[18:19]
	v_pk_mul_f32 v[70:71], v[12:13], v[18:19]
	v_sub_u32_e32 v12, 63, v11
	v_cndmask_b32_e32 v11, v12, v11, vcc
	v_lshlrev_b32_e32 v11, 6, v11
	v_add_lshl_u32 v12, v11, v57, 2
	v_add_u32_e32 v11, 0, v12
	v_add_u32_e32 v15, s0, v12
	v_or_b32_e32 v12, 13, v20
	v_sub_u32_e32 v13, 63, v12
	v_cndmask_b32_e32 v12, v13, v12, vcc
	v_lshlrev_b32_e32 v12, 6, v12
	v_add_lshl_u32 v13, v12, v57, 2
	v_add_u32_e32 v12, 0, v13
	v_add_u32_e32 v18, s0, v13
	v_or_b32_e32 v13, 14, v20
	v_sub_u32_e32 v14, 63, v13
	v_cndmask_b32_e32 v13, v14, v13, vcc
	v_lshlrev_b32_e32 v13, 6, v13
	v_add_lshl_u32 v14, v13, v57, 2
	v_add_u32_e32 v13, 0, v14
	v_add_u32_e32 v19, s0, v14
	v_or_b32_e32 v14, 15, v20
	v_sub_u32_e32 v20, 63, v14
	v_cndmask_b32_e32 v14, v20, v14, vcc
	v_mov_b32_e32 v68, v70
	v_lshlrev_b32_e32 v14, 6, v14
	s_waitcnt lgkmcnt(1)
	v_pk_mul_f32 v[70:71], v[70:71], v[62:63]
	v_add_lshl_u32 v20, v14, v57, 2
	v_lshlrev_b32_e32 v57, 6, v48
	s_waitcnt lgkmcnt(0)
	v_pk_mul_f32 v[70:71], v[70:71], v[64:65]
	v_pk_fma_f32 v[64:65], v[68:69], v[62:63], v[64:65]
	v_or3_b32 v52, v52, v57, v29
	v_mov_b32_e32 v71, v65
	v_add_u32_e32 v14, 0, v20
	v_add_u32_e32 v20, s0, v20
	ds_read_b32 v67, v11 offset:62720
	ds_read_b32 v73, v15
	ds_read_b32 v75, v12 offset:62720
	ds_read_b32 v77, v18
	ds_read_b32 v79, v13 offset:62720
	ds_read_b32 v81, v19
	ds_read_b32 v83, v14 offset:62720
	ds_read_b32 v85, v20
	v_lshl_add_u32 v57, v52, 3, 0
	s_waitcnt lgkmcnt(7)
	v_pk_mul_f32 v[64:65], v[70:71], v[66:67]
	v_mov_b32_e32 v52, v59
	v_mov_b32_e32 v72, v59
	v_pk_mul_f32 v[58:59], v[64:65], v[52:53]
	s_waitcnt lgkmcnt(6)
	v_pk_fma_f32 v[64:65], v[70:71], v[66:67], v[72:73]
	v_mov_b32_e32 v52, v61
	v_mov_b32_e32 v64, v58
	v_mov_b32_e32 v74, v61
	v_pk_mul_f32 v[58:59], v[58:59], v[52:53]
	v_mov_b32_e32 v52, v63
	v_mov_b32_e32 v76, v63
	v_pk_mul_f32 v[58:59], v[58:59], v[52:53]
	s_waitcnt lgkmcnt(4)
	v_pk_fma_f32 v[60:61], v[64:65], v[74:75], v[76:77]
	v_mov_b32_e32 v78, v67
	v_mov_b32_e32 v59, v61
	s_waitcnt lgkmcnt(3)
	v_pk_mul_f32 v[60:61], v[58:59], v[78:79]
	v_mov_b32_e32 v52, v75
	v_mov_b32_e32 v80, v75
	v_pk_mul_f32 v[60:61], v[60:61], v[52:53]
	s_waitcnt lgkmcnt(2)
	v_pk_fma_f32 v[58:59], v[58:59], v[78:79], v[80:81]
	v_mov_b32_e32 v52, v79
	v_mov_b32_e32 v58, v60
	v_mov_b32_e32 v82, v79
	v_pk_mul_f32 v[60:61], v[60:61], v[52:53]
	s_waitcnt lgkmcnt(1)
	v_mov_b32_e32 v52, v83
	v_mov_b32_e32 v84, v83
	v_pk_mul_f32 v[60:61], v[60:61], v[52:53]
	s_waitcnt lgkmcnt(0)
	v_pk_fma_f32 v[58:59], v[58:59], v[82:83], v[84:85]
	v_cmp_lt_i32_e32 vcc, 0, v33
	v_mov_b32_e32 v61, v59
	ds_write_b64 v57, v[60:61]
	s_waitcnt lgkmcnt(0)
	s_barrier
	s_and_saveexec_b64 s[0:1], vcc
	s_cbranch_execz .LBB0_713
	v_lshlrev_b32_e32 v29, 3, v29
	v_lshl_or_b32 v29, v48, 9, v29
	v_add_u32_e32 v29, 0, v29
	s_mov_b64 s[2:3], 0

; __device__ void rg_tile(unsigned char* lds, const Params& p, int l, int b, int ck, int hh, bool outmode) {
;     ...
;       float hc = car_pre;
;       for (int sgi = 0; sgi < seg; ++sgi) {
;         const float as = SEG[((sgi * 2 + d) * 64 + j) * 2 + 0], hs = SEG[((sgi * 2 + d) * 64 + j) * 2 + 1];
;         hc = as * hc + hs;
;       }
; #pragma unroll
;       for (int q = 0; q < 16; ++q) {
;         const int pos = seg * 16 + q;
;         const int tt = d == 0 ? pos : 63 - pos;
;         const float a = AA[(d * 64 + tt) * 64 + j];
;         hc = a * hc + BQ[(d * 64 + tt) * 64 + j];
;         AA[(d * 64 + tt) * 64 + j] = hc;
;       }
;     ...
;       const float v = hr * gelu_tanh(gp_pre[q]);
.LBB0_713:
	s_or_b64 exec, exec, s[0:1]
	ds_read_b32 v33, v0 offset:62720
	ds_read_b32 v1, v1
	s_mov_b32 s2, 0x13500
	v_readlane_b32 s0, v254, 9
	v_readlane_b32 s1, v254, 10
	s_mov_b32 s6, 0x3c800000
	s_waitcnt lgkmcnt(0)
	v_fmac_f32_e32 v1, v51, v33
	ds_write_b32 v0, v1 offset:62720
	ds_read_b32 v0, v16 offset:62720
	ds_read_b32 v22, v22
	v_ashrrev_i32_e32 v29, 31, v28
	v_lshlrev_b64 v[28:29], 11, v[28:29]
	v_mov_b32_e32 v239, 2
	s_waitcnt lgkmcnt(0)
	v_fmac_f32_e32 v22, v1, v0
	ds_write_b32 v16, v22 offset:62720
	ds_read_b32 v0, v23 offset:62720
	ds_read_b32 v1, v24
	s_waitcnt lgkmcnt(0)
	v_fmac_f32_e32 v1, v22, v0
	ds_write_b32 v23, v1 offset:62720
	ds_read_b32 v0, v25 offset:62720
	ds_read_b32 v16, v26
	v_lshlrev_b32_e32 v26, 8, v37
	v_add_u32_e32 v48, v30, v26
	s_waitcnt lgkmcnt(0)
	v_fmac_f32_e32 v16, v1, v0
	ds_write_b32 v25, v16 offset:62720
	ds_read_b32 v0, v27 offset:62720
	ds_read_b32 v1, v53
	v_lshlrev_b32_e32 v25, 11, v47
	s_waitcnt lgkmcnt(0)
	v_fmac_f32_e32 v1, v16, v0
	ds_write_b32 v27, v1 offset:62720
	ds_read_b32 v0, v54 offset:62720
	ds_read_b32 v22, v55
	v_add_u32_e32 v27, v30, v25
	v_add_u32_e32 v25, 0, v25
	v_add3_u32 v25, v25, v192, s2
	v_xor_b32_e32 v16, 0x80, v192
	s_waitcnt lgkmcnt(0)
	v_fmac_f32_e32 v22, v1, v0
	ds_write_b32 v54, v22 offset:62720
	ds_read_b32 v23, v2 offset:62720
	ds_read_b32 v24, v56
	v_lshlrev_b32_e32 v1, 16, v49
	v_lshlrev_b32_e32 v0, 16, v50
	v_mul_f32_e32 v33, 0x3d372713, v1
	v_mov_b32_e32 v47, v1
	s_waitcnt lgkmcnt(0)
	v_fmac_f32_e32 v24, v22, v23
	ds_write_b32 v2, v24 offset:62720
	ds_read_b32 v22, v17 offset:62720
	ds_read_b32 v23, v10
	v_lshlrev_b32_e32 v2, 8, v40
	v_lshlrev_b32_e32 v10, 8, v38
	v_add_u32_e32 v49, v30, v2
	v_add_u32_e32 v2, 0, v2
	s_waitcnt lgkmcnt(0)
	v_fmac_f32_e32 v23, v24, v22
	ds_write_b32 v17, v23 offset:62720
	ds_read_b32 v22, v3 offset:62720
	ds_read_b32 v24, v21
	v_lshlrev_b32_e32 v21, 8, v43
	v_lshlrev_b32_e32 v17, 8, v45
	v_add3_u32 v2, v2, v192, s2
	s_waitcnt lgkmcnt(0)
	v_fmac_f32_e32 v24, v23, v22
	ds_write_b32 v3, v24 offset:62720
	ds_read_b32 v3, v4 offset:62720
	ds_read_b32 v6, v6
	v_pk_mul_f32 v[22:23], v[0:1], 0.5 op_sel_hi:[1,0]
	v_mul_f32_e32 v1, v33, v1
	v_fmac_f32_e32 v47, v1, v47
	v_mov_b32_e32 v33, v193
	s_waitcnt lgkmcnt(0)
	v_fmac_f32_e32 v6, v24, v3
	ds_write_b32 v4, v6 offset:62720
	ds_read_b32 v3, v5 offset:62720
	ds_read_b32 v4, v7
	v_add_u32_e32 v7, 0, v26
	v_mul_f32_e32 v24, 0x3d372713, v0
	v_add_u32_e32 v26, v30, v10
	v_add_u32_e32 v10, 0, v10
	s_waitcnt lgkmcnt(0)
	v_fmac_f32_e32 v4, v6, v3
	ds_write_b32 v5, v4 offset:62720
	ds_read_b32 v3, v8 offset:62720
	ds_read_b32 v5, v9
	v_add_u32_e32 v6, v30, v21
	v_add_u32_e32 v9, v30, v17
	v_add3_u32 v10, v10, v192, s2
	s_waitcnt lgkmcnt(0)
	v_fmac_f32_e32 v5, v4, v3
	ds_write_b32 v8, v5 offset:62720
	ds_read_b32 v3, v11 offset:62720
	ds_read_b32 v4, v15
	v_add3_u32 v8, v7, v192, s2
	v_mul_f32_e32 v7, v24, v0
	v_fmac_f32_e32 v0, v7, v0
	v_mul_f32_e32 v0, 0x3f4c422a, v0
	s_waitcnt lgkmcnt(0)
	v_fmac_f32_e32 v4, v5, v3
	ds_write_b32 v11, v4 offset:62720
	ds_read_b32 v1, v12 offset:62720
	ds_read_b32 v3, v18
	v_mul_f32_e32 v5, 0x3f4c422a, v47
	v_add_f32_e32 v5, v5, v5
	v_add_f32_e32 v0, v0, v0
	v_mul_f32_e32 v5, 0x3fb8aa3b, v5
	s_waitcnt lgkmcnt(0)
	v_fmac_f32_e32 v3, v4, v1
	ds_write_b32 v12, v3 offset:62720
	ds_read_b32 v1, v13 offset:62720
	ds_read_b32 v4, v19
	v_mul_f32_e32 v0, 0x3fb8aa3b, v0
	v_exp_f32_e32 v5, v5
	v_exp_f32_e32 v0, v0
	v_xor_b32_e32 v47, 64, v192
	s_waitcnt lgkmcnt(0)
	v_fmac_f32_e32 v4, v3, v1
	ds_write_b32 v13, v4 offset:62720
	ds_read_b32 v1, v14 offset:62720
	ds_read_b32 v3, v20
	v_add_f32_e32 v5, 1.0, v5
	v_add_f32_e32 v0, 1.0, v0
	v_rcp_f32_e32 v5, v5
	v_rcp_f32_e32 v11, v0
	s_waitcnt lgkmcnt(0)
	v_fmac_f32_e32 v3, v4, v1
	ds_write_b32 v14, v3 offset:62720
	s_waitcnt lgkmcnt(0)
	s_barrier
; __device__ __forceinline__ bf16_t f2bf(float f) { return (bf16_t)(pack2(f, 0.f) & 0xffffu); }
; __device__ void rg_tile(unsigned char* lds, const Params& p, int l, int b, int ck, int hh, bool outmode) {
;     ...
;   if (outmode) {
;     const int ch = hh * 64 + lane;
;     const float gm = p.in[24][(size_t)l * 1024 + 768 + ch];
; #pragma unroll
;     for (int q = 0; q < 8; ++q) {
;       const int tt = w * 8 + q;
;       const int row = rowbase + t0 + tt;
;       const float hr = AA[tt * 64 + lane] + AA[(64 + tt) * 64 + lane];
;       const float v = hr * gelu_tanh(gp_pre[q]);
;       const float ss = wsum(v * v, lane);
;       const float rn = rsqrtf(ss * (1.f / 64.f) + EPSF);
;       y[(size_t)row * 1024 + 768 + ch] = f2bf(v * rn * gm);
;     }
;     __syncthreads();
;   }
	s_and_b32 s0, s13, 3
	v_bfe_u32 v208, v195, 4, 2
	v_and_b32_e32 v209, 15, v195
	s_lshl_b32 s1, s44, 11
	v_lshlrev_b32_e32 v210, 8, v208
	v_lshl_add_u32 v210, v209, 4, v210
	v_add_u32_e32 v210, s1, v210
	v_add_u32_e32 v210, 0xf500, v210
	ds_read_b128 v[212:215], v210
	ds_read_b128 v[216:219], v210 offset:16384
	ds_read_b128 v[154:157], v210 offset:1024
	ds_read_b128 v[158:161], v210 offset:17408
	v_readlane_b32 s2, v251, 31
	v_readlane_b32 s3, v251, 32
	s_add_i32 s4, s48, s45
	s_lshl_b32 s4, s4, 11
	s_lshl_b32 s5, s0, 7
	s_add_i32 s4, s4, s5
	s_addk_i32 s4, 0x600
	s_add_u32 s2, s2, s4
	s_addc_u32 s3, s3, 0
	v_lshlrev_b32_e32 v211, 11, v208
	v_lshl_add_u32 v211, v209, 3, v211
	v_lshlrev_b32_e32 v162, 16, v204
	v_and_b32_e32 v163, 0xffff0000, v204
	v_lshlrev_b32_e32 v164, 16, v205
	v_and_b32_e32 v165, 0xffff0000, v205
	v_lshlrev_b32_e32 v166, 16, v206
	v_and_b32_e32 v167, 0xffff0000, v206
	v_lshlrev_b32_e32 v168, 16, v207
	v_and_b32_e32 v169, 0xffff0000, v207
	v_mul_f32_e32 v170, 0x3d372713, v162
	v_mul_f32_e32 v171, 0x3d372713, v163
	v_mul_f32_e32 v172, 0x3d372713, v164
	v_mul_f32_e32 v173, 0x3d372713, v165
	v_mul_f32_e32 v174, 0x3d372713, v166
	v_mul_f32_e32 v175, 0x3d372713, v167
	v_mul_f32_e32 v176, 0x3d372713, v168
	v_mul_f32_e32 v177, 0x3d372713, v169
	v_mul_f32_e32 v170, v170, v162
	v_mul_f32_e32 v171, v171, v163
	v_mul_f32_e32 v172, v172, v164
	v_mul_f32_e32 v173, v173, v165
	v_mul_f32_e32 v174, v174, v166
	v_mul_f32_e32 v175, v175, v167
	v_mul_f32_e32 v176, v176, v168
	v_mul_f32_e32 v177, v177, v169
	v_fma_f32 v170, v170, v162, v162
	v_fma_f32 v171, v171, v163, v163
	v_fma_f32 v172, v172, v164, v164
	v_fma_f32 v173, v173, v165, v165
	v_fma_f32 v174, v174, v166, v166
	v_fma_f32 v175, v175, v167, v167
	v_fma_f32 v176, v176, v168, v168
	v_fma_f32 v177, v177, v169, v169
	v_mul_f32_e32 v170, 0x3f4c422a, v170
	v_mul_f32_e32 v171, 0x3f4c422a, v171
	v_mul_f32_e32 v172, 0x3f4c422a, v172
	v_mul_f32_e32 v173, 0x3f4c422a, v173
	v_mul_f32_e32 v174, 0x3f4c422a, v174
	v_mul_f32_e32 v175, 0x3f4c422a, v175
	v_mul_f32_e32 v176, 0x3f4c422a, v176
	v_mul_f32_e32 v177, 0x3f4c422a, v177
	v_add_f32_e32 v170, v170, v170
	v_add_f32_e32 v171, v171, v171
	v_add_f32_e32 v172, v172, v172
	v_add_f32_e32 v173, v173, v173
	v_add_f32_e32 v174, v174, v174
	v_add_f32_e32 v175, v175, v175
	v_add_f32_e32 v176, v176, v176
	v_add_f32_e32 v177, v177, v177
	v_mul_f32_e32 v170, 0x3fb8aa3b, v170
	v_mul_f32_e32 v171, 0x3fb8aa3b, v171
	v_mul_f32_e32 v172, 0x3fb8aa3b, v172
	v_mul_f32_e32 v173, 0x3fb8aa3b, v173
	v_mul_f32_e32 v174, 0x3fb8aa3b, v174
	v_mul_f32_e32 v175, 0x3fb8aa3b, v175
	v_mul_f32_e32 v176, 0x3fb8aa3b, v176
	v_mul_f32_e32 v177, 0x3fb8aa3b, v177
	v_exp_f32_e32 v170, v170
	v_exp_f32_e32 v171, v171
	v_exp_f32_e32 v172, v172
	v_exp_f32_e32 v173, v173
	v_exp_f32_e32 v174, v174
	v_exp_f32_e32 v175, v175
	v_exp_f32_e32 v176, v176
	v_exp_f32_e32 v177, v177
	v_add_f32_e32 v170, 1.0, v170
	v_add_f32_e32 v171, 1.0, v171
	v_add_f32_e32 v172, 1.0, v172
	v_add_f32_e32 v173, 1.0, v173
	v_add_f32_e32 v174, 1.0, v174
	v_add_f32_e32 v175, 1.0, v175
	v_add_f32_e32 v176, 1.0, v176
	v_add_f32_e32 v177, 1.0, v177
	v_rcp_f32_e32 v170, v170
	v_rcp_f32_e32 v171, v171
	v_rcp_f32_e32 v172, v172
	v_rcp_f32_e32 v173, v173
	v_rcp_f32_e32 v174, v174
	v_rcp_f32_e32 v175, v175
	v_rcp_f32_e32 v176, v176
	v_rcp_f32_e32 v177, v177
	v_mul_f32_e32 v162, 0.5, v162
	v_mul_f32_e32 v163, 0.5, v163
	v_mul_f32_e32 v164, 0.5, v164
	v_mul_f32_e32 v165, 0.5, v165
	v_mul_f32_e32 v166, 0.5, v166
	v_mul_f32_e32 v167, 0.5, v167
	v_mul_f32_e32 v168, 0.5, v168
	v_mul_f32_e32 v169, 0.5, v169
	v_fma_f32 v170, v170, -2.0, 1.0
	v_fma_f32 v171, v171, -2.0, 1.0
	v_fma_f32 v172, v172, -2.0, 1.0
	v_fma_f32 v173, v173, -2.0, 1.0
	v_fma_f32 v174, v174, -2.0, 1.0
	v_fma_f32 v175, v175, -2.0, 1.0
	v_fma_f32 v176, v176, -2.0, 1.0
	v_fma_f32 v177, v177, -2.0, 1.0
	v_add_f32_e32 v170, 1.0, v170
	v_add_f32_e32 v171, 1.0, v171
	v_add_f32_e32 v172, 1.0, v172
	v_add_f32_e32 v173, 1.0, v173
	v_add_f32_e32 v174, 1.0, v174
	v_add_f32_e32 v175, 1.0, v175
	v_add_f32_e32 v176, 1.0, v176
	v_add_f32_e32 v177, 1.0, v177
	v_mul_f32_e32 v170, v162, v170
	v_mul_f32_e32 v171, v163, v171
	v_mul_f32_e32 v172, v164, v172
	v_mul_f32_e32 v173, v165, v173
	v_mul_f32_e32 v174, v166, v174
	v_mul_f32_e32 v175, v167, v175
	v_mul_f32_e32 v176, v168, v176
	v_mul_f32_e32 v177, v169, v177
	s_waitcnt lgkmcnt(0)
	v_add_f32_e32 v212, v212, v216
	v_add_f32_e32 v213, v213, v217
	v_add_f32_e32 v214, v214, v218
	v_add_f32_e32 v215, v215, v219
	v_add_f32_e32 v154, v154, v158
	v_add_f32_e32 v155, v155, v159
	v_add_f32_e32 v156, v156, v160
	v_add_f32_e32 v157, v157, v161
	v_mul_f32_e32 v178, v212, v170
	v_mul_f32_e32 v179, v213, v171
	v_mul_f32_e32 v180, v214, v172
	v_mul_f32_e32 v181, v215, v173
	v_mul_f32_e32 v182, v154, v174
	v_mul_f32_e32 v183, v155, v175
	v_mul_f32_e32 v184, v156, v176
	v_mul_f32_e32 v185, v157, v177
	v_mul_f32_e32 v186, v178, v178
	v_mul_f32_e32 v187, v182, v182
	v_fmac_f32_e32 v186, v179, v179
	v_fmac_f32_e32 v187, v183, v183
	v_fmac_f32_e32 v186, v180, v180
	v_fmac_f32_e32 v187, v184, v184
	v_fmac_f32_e32 v186, v181, v181
	v_fmac_f32_e32 v187, v185, v185
	s_nop 1
	v_add_f32_dpp v186, v186, v186 quad_perm:[1,0,3,2] row_mask:0xf bank_mask:0xf
	v_add_f32_dpp v187, v187, v187 quad_perm:[1,0,3,2] row_mask:0xf bank_mask:0xf
	s_nop 0
	v_add_f32_dpp v186, v186, v186 quad_perm:[2,3,0,1] row_mask:0xf bank_mask:0xf
	v_add_f32_dpp v187, v187, v187 quad_perm:[2,3,0,1] row_mask:0xf bank_mask:0xf
	s_nop 0
	v_add_f32_dpp v186, v186, v186 row_half_mirror row_mask:0xf bank_mask:0xf
	v_add_f32_dpp v187, v187, v187 row_half_mirror row_mask:0xf bank_mask:0xf
	s_nop 0
	v_add_f32_dpp v186, v186, v186 row_mirror row_mask:0xf bank_mask:0xf
	v_add_f32_dpp v187, v187, v187 row_mirror row_mask:0xf bank_mask:0xf
	s_nop 0
	v_fmamk_f32 v188, v186, 0x3c800000, v194
	v_fmamk_f32 v189, v187, 0x3c800000, v194
	v_rsq_f32_e32 v188, v188
	v_rsq_f32_e32 v189, v189
	s_nop 0
	v_mul_f32_e32 v178, v178, v188
	v_mul_f32_e32 v179, v179, v188
	v_mul_f32_e32 v180, v180, v188
	v_mul_f32_e32 v181, v181, v188
	v_mul_f32_e32 v182, v182, v189
	v_mul_f32_e32 v183, v183, v189
	v_mul_f32_e32 v184, v184, v189
	v_mul_f32_e32 v185, v185, v189
	v_mul_f32_e32 v178, v178, v200
	v_mul_f32_e32 v179, v179, v201
	v_mul_f32_e32 v180, v180, v202
	v_mul_f32_e32 v181, v181, v203
	v_mul_f32_e32 v182, v182, v200
	v_mul_f32_e32 v183, v183, v201
	v_mul_f32_e32 v184, v184, v202
	v_mul_f32_e32 v185, v185, v203
	v_cvt_pk_bf16_f32 v212, v178, v179
	v_cvt_pk_bf16_f32 v213, v180, v181
	v_cvt_pk_bf16_f32 v154, v182, v183
	v_cvt_pk_bf16_f32 v155, v184, v185
	global_store_dwordx2 v211, v[212:213], s[2:3]
	v_add_u32_e32 v211, 0x2000, v211
	global_store_dwordx2 v211, v[154:155], s[2:3]
	s_barrier
	s_mov_b64 s[0:1], 0
